# convert write phase: LDS staging writes paired into ds_write2_b32 (half the LDS write instructions)
# baseline (speedup 1.0000x reference)
;     ...
;     for (int i = 0; i < 32; ++i) { const int kk = 2 * i + (lane >> 5); wv[i] = W[(size_t)(k0 + kk) * N + n0 + (lane & 31)]; }
; #pragma unroll
;     for (int i = 0; i < 32; ++i) { const int kk = 2 * i + (lane >> 5); scr[kk * 33 + (lane & 31)] = wv[i]; }
; __device__ __forceinline__ void phase_convert_weights(const Args& a, int l, LAS unsigned char* lds) {
;     ...
;     for (int it = gw; it < NITEMS; it += NGW) {
;         int r = it;
;         if (r < 2 * I_UP) {
;             const int which = r / I_UP; r -= which * I_UP;
;             const float* W = a.in[which ? I_UP2 : I_UP1] + (size_t)l * DM * NUP; bf16_t* WT = (bf16_t*)(ws + (which ? W_UP2 : W_UP1));
;             const int kb = r / 176, n0 = (r % 176) * 32, half = n0 / DFF, j = n0 % DFF;
;             transpose_item(W, DM, NUP, WT, kb, n0, 256 * (j / 128) + 128 * half + (j % 128), scr, lane); continue; }
.LBB0_488:
	s_mov_b64 s[16:17], exec
	v_readlane_b32 s48, v255, 7
	v_readlane_b32 s49, v255, 8
	v_readlane_b32 s19, v255, 15
	v_and_b32_e32 v0, 63, v196
	v_lshrrev_b32_e32 v7, 6, v196
	v_lshrrev_b32_e32 v1, 3, v0
	v_and_b32_e32 v2, 7, v0
	v_readfirstlane_b32 s24, v7
	v_lshlrev_b32_e32 v7, 14, v7
	v_mul_u32_u24_e32 v3, 33, v1
	v_lshl_add_u32 v3, v2, 2, v3
	v_lshl_add_u32 v3, v3, 2, v7
	v_add_u32_e32 v52, 0x420, v3
	v_add_u32_e32 v53, 0x840, v3
	v_add_u32_e32 v54, 0xc60, v3
	v_add_u32_e32 v55, 0x1080, v3
	v_add_u32_e32 v56, 0x14a0, v3
	v_add_u32_e32 v57, 0x18c0, v3
	v_add_u32_e32 v58, 0x1ce0, v3
	v_mul_u32_u24_e32 v4, 0x108, v2
	v_add_u32_e32 v4, v4, v1
	v_lshl_add_u32 v4, v4, 2, v7
	v_lshlrev_b32_e32 v2, 4, v2
	s_lshl_b32 s0, s2, 3
	s_add_i32 s24, s24, s0
	s_cmpk_ge_i32 s24, 0x3300
	s_cbranch_scc1 .Lcv_done
	s_mov_b32 s42, 1.0
	s_cmpk_ge_i32 s24, 0x1600
	s_cbranch_scc1 .Lcv_notup1
	s_cmpk_ge_i32 s24, 0xb00
	s_cselect_b32 s26, 1, 0
	s_mulk_i32 s26, 0xb00
	s_sub_i32 s25, s24, s26
	s_cmp_lg_u32 s26, 0
	s_cselect_b32 s43, 0xa0, 0x28
	s_mov_b32 s52, 0x800000
	s_cselect_b32 s52, 0x2980000, s52
	s_mul_i32 s27, s25, 0xba2f
	s_lshr_b32 s27, s27, 23
	s_mul_i32 s0, s27, 176
	s_sub_i32 s28, s25, s0
	s_lshl_b32 s28, s28, 5
	s_cmpk_ge_i32 s28, 0xb00
	s_cselect_b32 s0, 0xb00, 0
	s_cselect_b32 s1, 128, 0
	s_sub_i32 s0, s28, s0
	s_lshr_b32 s29, s0, 7
	s_lshl_b32 s29, s29, 8
	s_and_b32 s0, s0, 127
	s_add_i32 s29, s29, s0
	s_add_i32 s29, s29, s1
	s_mul_i32 s51, s19, 0x1600000
	s_movk_i32 s36, 0x5800
	s_movk_i32 s37, 0x800
	s_branch .Lcv_common1

;     ...
;     for (int i = 0; i < 32; ++i) { const int kk = 2 * i + (lane >> 5); wv[i] = W[(size_t)(k0 + kk) * N + n0 + (lane & 31)]; }
; #pragma unroll
;     for (int i = 0; i < 32; ++i) { const int kk = 2 * i + (lane >> 5); scr[kk * 33 + (lane & 31)] = wv[i]; }
; __device__ __forceinline__ void phase_convert_weights(const Args& a, int l, LAS unsigned char* lds) {
;     ...
;     for (int it = gw; it < NITEMS; it += NGW) {
;         int r = it;
;         if (r < 2 * I_UP) {
;             const int which = r / I_UP; r -= which * I_UP;
;             const float* W = a.in[which ? I_UP2 : I_UP1] + (size_t)l * DM * NUP; bf16_t* WT = (bf16_t*)(ws + (which ? W_UP2 : W_UP1));
;             const int kb = r / 176, n0 = (r % 176) * 32, half = n0 / DFF, j = n0 % DFF;
;             transpose_item(W, DM, NUP, WT, kb, n0, 256 * (j / 128) + 128 * half + (j % 128), scr, lane); continue; }
.Lcv_loop:
	s_mov_b64 s[56:57], s[34:35]
	s_mov_b32 s53, s37
	s_mov_b32 s50, s42
	ds_write2_b32 v3, v8, v9 offset0:0 offset1:1
	ds_write2_b32 v3, v10, v11 offset0:2 offset1:3
	ds_write2_b32 v52, v12, v13 offset0:0 offset1:1
	ds_write2_b32 v52, v14, v15 offset0:2 offset1:3
	ds_write2_b32 v53, v16, v17 offset0:0 offset1:1
	ds_write2_b32 v53, v18, v19 offset0:2 offset1:3
	ds_write2_b32 v54, v20, v21 offset0:0 offset1:1
	ds_write2_b32 v54, v22, v23 offset0:2 offset1:3
	ds_write2_b32 v55, v24, v25 offset0:0 offset1:1
	ds_write2_b32 v55, v26, v27 offset0:2 offset1:3
	ds_write2_b32 v56, v28, v29 offset0:0 offset1:1
	ds_write2_b32 v56, v30, v31 offset0:2 offset1:3
	ds_write2_b32 v57, v32, v33 offset0:0 offset1:1
	ds_write2_b32 v57, v34, v35 offset0:2 offset1:3
	ds_write2_b32 v58, v36, v37 offset0:0 offset1:1
	ds_write2_b32 v58, v38, v39 offset0:2 offset1:3
	s_addk_i32 s24, 0x800
	s_cmpk_ge_i32 s24, 0x3300
	s_cbranch_scc1 .Lcv_nonext
	s_mov_b32 s42, 1.0
	s_cmpk_ge_i32 s24, 0x1600
	s_cbranch_scc1 .Lcv_notup2
	s_cmpk_ge_i32 s24, 0xb00
	s_cselect_b32 s26, 1, 0
	s_mulk_i32 s26, 0xb00
	s_sub_i32 s25, s24, s26
	s_cmp_lg_u32 s26, 0
	s_cselect_b32 s43, 0xa0, 0x28
	s_mov_b32 s52, 0x800000
	s_cselect_b32 s52, 0x2980000, s52
	s_mul_i32 s27, s25, 0xba2f
	s_lshr_b32 s27, s27, 23
	s_mul_i32 s0, s27, 176
	s_sub_i32 s28, s25, s0
	s_lshl_b32 s28, s28, 5
	s_cmpk_ge_i32 s28, 0xb00
	s_cselect_b32 s0, 0xb00, 0
	s_cselect_b32 s1, 128, 0
	s_sub_i32 s0, s28, s0
	s_lshr_b32 s29, s0, 7
	s_lshl_b32 s29, s29, 8
	s_and_b32 s0, s0, 127
	s_add_i32 s29, s29, s0
	s_add_i32 s29, s29, s1
	s_mul_i32 s51, s19, 0x1600000
	s_movk_i32 s36, 0x5800
	s_movk_i32 s37, 0x800
	s_branch .Lcv_common2
